# loop-edge hoists extended to the in-proj bf16 K-loop (around the zero-tile skip labels) and the down-proj pointer copy
# baseline (speedup 1.0000x reference)
.Lt13a_3:
	s_add_i32 s43, s43, 2
	s_add_u32 s6, s6, 0x100
	s_addc_u32 s7, s7, 0
	s_setprio 0
	s_setprio 1
	s_cmp_lg_u32 s100, 0
	s_cbranch_scc1 .Lt13b_3
	v_mfma_f32_16x16x32_bf16 v[56:59], v[160:163], v[176:179], v[56:59]
	v_mfma_f32_16x16x32_bf16 v[56:59], v[164:167], v[180:183], v[56:59]
	v_mfma_f32_16x16x32_bf16 v[40:43], v[160:163], v[184:187], v[40:43]
	v_mfma_f32_16x16x32_bf16 v[40:43], v[164:167], v[188:191], v[40:43]
	v_mfma_f32_16x16x32_bf16 v[24:27], v[160:163], v[192:195], v[24:27]
	v_mfma_f32_16x16x32_bf16 v[24:27], v[164:167], v[196:199], v[24:27]
	v_mfma_f32_16x16x32_bf16 v[8:11], v[160:163], v[200:203], v[8:11]
	v_mfma_f32_16x16x32_bf16 v[8:11], v[164:167], v[204:207], v[8:11]
	v_mfma_f32_16x16x32_bf16 v[4:7], v[168:171], v[200:203], v[4:7]
	v_mfma_f32_16x16x32_bf16 v[4:7], v[172:175], v[204:207], v[4:7]
	v_mfma_f32_16x16x32_bf16 v[20:23], v[168:171], v[192:195], v[20:23]
	v_mfma_f32_16x16x32_bf16 v[20:23], v[172:175], v[196:199], v[20:23]
	v_mfma_f32_16x16x32_bf16 v[36:39], v[168:171], v[184:187], v[36:39]
	v_mfma_f32_16x16x32_bf16 v[36:39], v[172:175], v[188:191], v[36:39]
	v_mfma_f32_16x16x32_bf16 v[52:55], v[168:171], v[176:179], v[52:55]
	v_mfma_f32_16x16x32_bf16 v[52:55], v[172:175], v[180:183], v[52:55]
.Lt13b_3:
	s_cmp_gt_u32 s43, 29
	s_barrier
	s_setprio 0
	s_cbranch_scc0 .LBB0_1516
	s_cmpk_lt_u32 s21, 0x100
	s_cbranch_scc0 .LBB0_1519
	s_barrier

.LBB0_3195:
	v_add_u32_e32 v144, s26, v249
	v_add_u32_e32 v160, s38, v249
	ds_read_b128 v[132:135], v144
	ds_read_b128 v[136:139], v144 offset:1024
	ds_read_b128 v[140:143], v144 offset:2048
	ds_read_b128 v[144:147], v144 offset:3072
	ds_read_b128 v[148:151], v160
	ds_read_b128 v[152:155], v160 offset:1024
	ds_read_b128 v[156:159], v160 offset:2048
	ds_read_b128 v[160:163], v160 offset:3072
	s_add_u32 s24, s14, 0x100
	s_addc_u32 s25, s15, 0
	s_cmpk_eq_i32 s74, 0x54
	s_cselect_b32 s35, s5, s25
	s_cselect_b32 s34, s4, s24
	s_cselect_b32 s19, s13, s73
	s_cselect_b32 s18, s12, s71
	v_lshl_add_u64 v[196:197], s[14:15], 0, v[222:223]
	s_add_i32 m0, s41, 0xc000
	ds_read_b128 v[164:167], v250
	ds_read_b128 v[168:171], v250 offset:1024
	ds_read_b128 v[172:175], v250 offset:2048
	ds_read_b128 v[176:179], v250 offset:3072
	ds_read_b128 v[180:183], v250 offset:4096
	ds_read_b128 v[184:187], v250 offset:5120
	ds_read_b128 v[188:191], v250 offset:6144
	ds_read_b128 v[192:195], v250 offset:7168
	global_load_lds_dwordx4 v[196:197], off
	v_lshl_add_u64 v[196:197], s[14:15], 0, v[224:225]
	s_add_i32 m0, s41, 0xe000
	s_nop 0
	global_load_lds_dwordx4 v[196:197], off
	s_setprio 1
	s_waitcnt vmcnt(8)
	s_waitcnt lgkmcnt(0)
	s_barrier
	v_mfma_f32_16x16x32_bf16 v[128:131], v[132:135], v[164:167], v[128:131]
	v_mfma_f32_16x16x32_bf16 v[128:131], v[136:139], v[168:171], v[128:131]
	v_mfma_f32_16x16x32_bf16 v[112:115], v[132:135], v[172:175], v[112:115]
	v_mfma_f32_16x16x32_bf16 v[112:115], v[136:139], v[176:179], v[112:115]
	v_mfma_f32_16x16x32_bf16 v[96:99], v[132:135], v[180:183], v[96:99]
	v_mfma_f32_16x16x32_bf16 v[96:99], v[136:139], v[184:187], v[96:99]
	v_mfma_f32_16x16x32_bf16 v[80:83], v[132:135], v[188:191], v[80:83]
	v_mfma_f32_16x16x32_bf16 v[80:83], v[136:139], v[192:195], v[80:83]
	v_mfma_f32_16x16x32_bf16 v[76:79], v[140:143], v[188:191], v[76:79]
	v_mfma_f32_16x16x32_bf16 v[76:79], v[144:147], v[192:195], v[76:79]
	v_mfma_f32_16x16x32_bf16 v[92:95], v[140:143], v[180:183], v[92:95]
	v_mfma_f32_16x16x32_bf16 v[92:95], v[144:147], v[184:187], v[92:95]
	v_mfma_f32_16x16x32_bf16 v[108:111], v[140:143], v[172:175], v[108:111]
	v_mfma_f32_16x16x32_bf16 v[108:111], v[144:147], v[176:179], v[108:111]
	v_mfma_f32_16x16x32_bf16 v[124:127], v[140:143], v[164:167], v[124:127]
	v_mfma_f32_16x16x32_bf16 v[124:127], v[144:147], v[168:171], v[124:127]
	s_setprio 0
	s_setprio 1
	v_mfma_f32_16x16x32_bf16 v[120:123], v[148:151], v[164:167], v[120:123]
	v_mfma_f32_16x16x32_bf16 v[120:123], v[152:155], v[168:171], v[120:123]
	v_mfma_f32_16x16x32_bf16 v[104:107], v[148:151], v[172:175], v[104:107]
	v_mfma_f32_16x16x32_bf16 v[104:107], v[152:155], v[176:179], v[104:107]
	v_mfma_f32_16x16x32_bf16 v[88:91], v[148:151], v[180:183], v[88:91]
	v_mfma_f32_16x16x32_bf16 v[88:91], v[152:155], v[184:187], v[88:91]
	v_mfma_f32_16x16x32_bf16 v[72:75], v[148:151], v[188:191], v[72:75]
	v_mfma_f32_16x16x32_bf16 v[72:75], v[152:155], v[192:195], v[72:75]
	v_mfma_f32_16x16x32_bf16 v[68:71], v[156:159], v[188:191], v[68:71]
	v_mfma_f32_16x16x32_bf16 v[68:71], v[160:163], v[192:195], v[68:71]
	v_mfma_f32_16x16x32_bf16 v[84:87], v[156:159], v[180:183], v[84:87]
	v_mfma_f32_16x16x32_bf16 v[84:87], v[160:163], v[184:187], v[84:87]
	v_mfma_f32_16x16x32_bf16 v[100:103], v[156:159], v[172:175], v[100:103]
	v_mfma_f32_16x16x32_bf16 v[100:103], v[160:163], v[176:179], v[100:103]
	v_mfma_f32_16x16x32_bf16 v[116:119], v[156:159], v[164:167], v[116:119]
	v_mfma_f32_16x16x32_bf16 v[116:119], v[160:163], v[168:171], v[116:119]
	s_barrier
	s_setprio 0
	s_mov_b32 m0, s27
	v_lshl_add_u64 v[196:197], s[18:19], 0, v[2:3]
	s_add_u32 s14, s18, 0x160000
	ds_read_b128 v[164:167], v250 offset:16384
	ds_read_b128 v[168:171], v250 offset:17408
	ds_read_b128 v[172:175], v250 offset:18432
	ds_read_b128 v[176:179], v250 offset:19456
	ds_read_b128 v[180:183], v250 offset:20480
	ds_read_b128 v[184:187], v250 offset:21504
	ds_read_b128 v[188:191], v250 offset:22528
	ds_read_b128 v[192:195], v250 offset:23552
	global_load_lds_dwordx4 v[196:197], off
	v_lshl_add_u64 v[198:199], s[18:19], 0, v[216:217]
	s_mov_b32 m0, s37
	s_addc_u32 s15, s19, 0
	global_load_lds_dwordx4 v[198:199], off
	v_lshl_add_u64 v[200:201], s[14:15], 0, v[2:3]
	s_mov_b32 m0, s39
	v_lshl_add_u64 v[202:203], s[34:35], 0, v[218:219]
	global_load_lds_dwordx4 v[200:201], off
	v_lshl_add_u64 v[200:201], s[14:15], 0, v[216:217]
	s_mov_b32 m0, s40
	s_nop 0
	global_load_lds_dwordx4 v[200:201], off
	v_lshl_add_u64 v[200:201], s[34:35], 0, v[220:221]
	s_mov_b32 m0, s41
	s_nop 0
	global_load_lds_dwordx4 v[200:201], off
	s_mov_b32 m0, s42
	s_nop 0
	global_load_lds_dwordx4 v[202:203], off
	s_setprio 1
	s_waitcnt vmcnt(8)
	s_waitcnt lgkmcnt(0)
	s_barrier
	v_mfma_f32_16x16x32_bf16 v[64:67], v[132:135], v[164:167], v[64:67]
	v_mfma_f32_16x16x32_bf16 v[64:67], v[136:139], v[168:171], v[64:67]
	v_mfma_f32_16x16x32_bf16 v[48:51], v[132:135], v[172:175], v[48:51]
	v_mfma_f32_16x16x32_bf16 v[48:51], v[136:139], v[176:179], v[48:51]
	v_mfma_f32_16x16x32_bf16 v[32:35], v[132:135], v[180:183], v[32:35]
	v_mfma_f32_16x16x32_bf16 v[32:35], v[136:139], v[184:187], v[32:35]
	v_mfma_f32_16x16x32_bf16 v[16:19], v[132:135], v[188:191], v[16:19]
	v_mfma_f32_16x16x32_bf16 v[16:19], v[136:139], v[192:195], v[16:19]
	v_mfma_f32_16x16x32_bf16 v[12:15], v[140:143], v[188:191], v[12:15]
	v_mfma_f32_16x16x32_bf16 v[12:15], v[144:147], v[192:195], v[12:15]
	v_mfma_f32_16x16x32_bf16 v[28:31], v[140:143], v[180:183], v[28:31]
	v_mfma_f32_16x16x32_bf16 v[28:31], v[144:147], v[184:187], v[28:31]
	v_mfma_f32_16x16x32_bf16 v[44:47], v[140:143], v[172:175], v[44:47]
	v_mfma_f32_16x16x32_bf16 v[44:47], v[144:147], v[176:179], v[44:47]
	v_mfma_f32_16x16x32_bf16 v[60:63], v[140:143], v[164:167], v[60:63]
	v_mfma_f32_16x16x32_bf16 v[60:63], v[144:147], v[168:171], v[60:63]
	s_setprio 0
	s_setprio 1
	v_mfma_f32_16x16x32_bf16 v[56:59], v[148:151], v[164:167], v[56:59]
	v_mfma_f32_16x16x32_bf16 v[56:59], v[152:155], v[168:171], v[56:59]
	v_mfma_f32_16x16x32_bf16 v[40:43], v[148:151], v[172:175], v[40:43]
	v_mfma_f32_16x16x32_bf16 v[40:43], v[152:155], v[176:179], v[40:43]
	v_mfma_f32_16x16x32_bf16 v[24:27], v[148:151], v[180:183], v[24:27]
	v_mfma_f32_16x16x32_bf16 v[24:27], v[152:155], v[184:187], v[24:27]
	v_mfma_f32_16x16x32_bf16 v[8:11], v[148:151], v[188:191], v[8:11]
	v_mfma_f32_16x16x32_bf16 v[8:11], v[152:155], v[192:195], v[8:11]
	v_mfma_f32_16x16x32_bf16 v[4:7], v[156:159], v[188:191], v[4:7]
	v_mfma_f32_16x16x32_bf16 v[4:7], v[160:163], v[192:195], v[4:7]
	v_mfma_f32_16x16x32_bf16 v[20:23], v[156:159], v[180:183], v[20:23]
	v_mfma_f32_16x16x32_bf16 v[20:23], v[160:163], v[184:187], v[20:23]
	v_mfma_f32_16x16x32_bf16 v[36:39], v[156:159], v[172:175], v[36:39]
	v_mfma_f32_16x16x32_bf16 v[36:39], v[160:163], v[176:179], v[36:39]
	v_mfma_f32_16x16x32_bf16 v[52:55], v[156:159], v[164:167], v[52:55]
	v_mfma_f32_16x16x32_bf16 v[52:55], v[160:163], v[168:171], v[52:55]
	s_barrier
	s_setprio 0
	v_add_u32_e32 v144, s49, v249
	v_add_u32_e32 v160, s56, v249
	ds_read_b128 v[132:135], v144
	ds_read_b128 v[136:139], v144 offset:1024
	ds_read_b128 v[140:143], v144 offset:2048
	ds_read_b128 v[144:147], v144 offset:3072
	ds_read_b128 v[148:151], v160
	ds_read_b128 v[152:155], v160 offset:1024
	ds_read_b128 v[156:159], v160 offset:2048
	ds_read_b128 v[160:163], v160 offset:3072
	s_add_u32 s14, s34, 0x160000
	s_addc_u32 s15, s35, 0
	s_mov_b32 m0, s43
	v_lshl_add_u64 v[204:205], s[14:15], 0, v[220:221]
	ds_read_b128 v[164:167], v250 offset:32768
	ds_read_b128 v[168:171], v250 offset:33792
	ds_read_b128 v[172:175], v250 offset:34816
	ds_read_b128 v[176:179], v250 offset:35840
	ds_read_b128 v[180:183], v250 offset:36864
	ds_read_b128 v[184:187], v250 offset:37888
	ds_read_b128 v[188:191], v250 offset:38912
	ds_read_b128 v[192:195], v250 offset:39936
	global_load_lds_dwordx4 v[204:205], off
	v_lshl_add_u64 v[204:205], s[14:15], 0, v[218:219]
	s_mov_b32 m0, s44
	s_nop 0
	global_load_lds_dwordx4 v[204:205], off
	s_setprio 1
	s_waitcnt vmcnt(8)
	s_waitcnt lgkmcnt(0)
	s_barrier
	v_mfma_f32_16x16x32_bf16 v[128:131], v[132:135], v[164:167], v[128:131]
	v_mfma_f32_16x16x32_bf16 v[128:131], v[136:139], v[168:171], v[128:131]
	v_mfma_f32_16x16x32_bf16 v[112:115], v[132:135], v[172:175], v[112:115]
	v_mfma_f32_16x16x32_bf16 v[112:115], v[136:139], v[176:179], v[112:115]
	v_mfma_f32_16x16x32_bf16 v[96:99], v[132:135], v[180:183], v[96:99]
	v_mfma_f32_16x16x32_bf16 v[96:99], v[136:139], v[184:187], v[96:99]
	v_mfma_f32_16x16x32_bf16 v[80:83], v[132:135], v[188:191], v[80:83]
	v_mfma_f32_16x16x32_bf16 v[80:83], v[136:139], v[192:195], v[80:83]
	v_mfma_f32_16x16x32_bf16 v[76:79], v[140:143], v[188:191], v[76:79]
	v_mfma_f32_16x16x32_bf16 v[76:79], v[144:147], v[192:195], v[76:79]
	v_mfma_f32_16x16x32_bf16 v[92:95], v[140:143], v[180:183], v[92:95]
	v_mfma_f32_16x16x32_bf16 v[92:95], v[144:147], v[184:187], v[92:95]
	v_mfma_f32_16x16x32_bf16 v[108:111], v[140:143], v[172:175], v[108:111]
	v_mfma_f32_16x16x32_bf16 v[108:111], v[144:147], v[176:179], v[108:111]
	v_mfma_f32_16x16x32_bf16 v[124:127], v[140:143], v[164:167], v[124:127]
	v_mfma_f32_16x16x32_bf16 v[124:127], v[144:147], v[168:171], v[124:127]
	s_setprio 0
	s_setprio 1
	v_mfma_f32_16x16x32_bf16 v[120:123], v[148:151], v[164:167], v[120:123]
	v_mfma_f32_16x16x32_bf16 v[120:123], v[152:155], v[168:171], v[120:123]
	v_mfma_f32_16x16x32_bf16 v[104:107], v[148:151], v[172:175], v[104:107]
	v_mfma_f32_16x16x32_bf16 v[104:107], v[152:155], v[176:179], v[104:107]
	v_mfma_f32_16x16x32_bf16 v[88:91], v[148:151], v[180:183], v[88:91]
	v_mfma_f32_16x16x32_bf16 v[88:91], v[152:155], v[184:187], v[88:91]
	v_mfma_f32_16x16x32_bf16 v[72:75], v[148:151], v[188:191], v[72:75]
	v_mfma_f32_16x16x32_bf16 v[72:75], v[152:155], v[192:195], v[72:75]
	v_mfma_f32_16x16x32_bf16 v[68:71], v[156:159], v[188:191], v[68:71]
	v_mfma_f32_16x16x32_bf16 v[68:71], v[160:163], v[192:195], v[68:71]
	v_mfma_f32_16x16x32_bf16 v[84:87], v[156:159], v[180:183], v[84:87]
	v_mfma_f32_16x16x32_bf16 v[84:87], v[160:163], v[184:187], v[84:87]
	v_mfma_f32_16x16x32_bf16 v[100:103], v[156:159], v[172:175], v[100:103]
	v_mfma_f32_16x16x32_bf16 v[100:103], v[160:163], v[176:179], v[100:103]
	v_mfma_f32_16x16x32_bf16 v[116:119], v[156:159], v[164:167], v[116:119]
	v_mfma_f32_16x16x32_bf16 v[116:119], v[160:163], v[168:171], v[116:119]
	s_barrier
	s_setprio 0
	s_mov_b32 m0, s50
	v_lshl_add_u64 v[196:197], v[196:197], 0, s[64:65]
	s_add_u32 s14, s18, 0x160080
	ds_read_b128 v[164:167], v250 offset:49152
	ds_read_b128 v[168:171], v250 offset:50176
	ds_read_b128 v[172:175], v250 offset:51200
	ds_read_b128 v[176:179], v250 offset:52224
	ds_read_b128 v[180:183], v250 offset:53248
	ds_read_b128 v[184:187], v250 offset:54272
	ds_read_b128 v[188:191], v250 offset:55296
	ds_read_b128 v[192:195], v250 offset:56320
	global_load_lds_dwordx4 v[196:197], off
	v_lshl_add_u64 v[196:197], v[198:199], 0, s[64:65]
	s_mov_b32 m0, s51
	s_addc_u32 s15, s19, 0
	global_load_lds_dwordx4 v[196:197], off
	v_lshl_add_u64 v[196:197], s[14:15], 0, v[2:3]
	s_mov_b32 m0, s57
	s_nop 0
	global_load_lds_dwordx4 v[196:197], off
	v_lshl_add_u64 v[196:197], s[14:15], 0, v[216:217]
	s_mov_b32 m0, s58
	s_nop 0
	global_load_lds_dwordx4 v[196:197], off
	v_lshl_add_u64 v[196:197], v[200:201], 0, s[64:65]
	s_mov_b32 m0, s52
	s_nop 0
	global_load_lds_dwordx4 v[196:197], off
	v_lshl_add_u64 v[196:197], v[202:203], 0, s[64:65]
	s_mov_b32 m0, s53
	s_nop 0
	global_load_lds_dwordx4 v[196:197], off
	s_setprio 1
	s_waitcnt vmcnt(8)
	s_waitcnt lgkmcnt(0)
	s_barrier
	v_mfma_f32_16x16x32_bf16 v[64:67], v[132:135], v[164:167], v[64:67]
	v_mfma_f32_16x16x32_bf16 v[64:67], v[136:139], v[168:171], v[64:67]
	v_mfma_f32_16x16x32_bf16 v[48:51], v[132:135], v[172:175], v[48:51]
	v_mfma_f32_16x16x32_bf16 v[48:51], v[136:139], v[176:179], v[48:51]
	v_mfma_f32_16x16x32_bf16 v[32:35], v[132:135], v[180:183], v[32:35]
	v_mfma_f32_16x16x32_bf16 v[32:35], v[136:139], v[184:187], v[32:35]
	v_mfma_f32_16x16x32_bf16 v[16:19], v[132:135], v[188:191], v[16:19]
	v_mfma_f32_16x16x32_bf16 v[16:19], v[136:139], v[192:195], v[16:19]
	v_mfma_f32_16x16x32_bf16 v[12:15], v[140:143], v[188:191], v[12:15]
	v_mfma_f32_16x16x32_bf16 v[12:15], v[144:147], v[192:195], v[12:15]
	v_mfma_f32_16x16x32_bf16 v[28:31], v[140:143], v[180:183], v[28:31]
	v_mfma_f32_16x16x32_bf16 v[28:31], v[144:147], v[184:187], v[28:31]
	v_mfma_f32_16x16x32_bf16 v[44:47], v[140:143], v[172:175], v[44:47]
	v_mfma_f32_16x16x32_bf16 v[44:47], v[144:147], v[176:179], v[44:47]
	v_mfma_f32_16x16x32_bf16 v[60:63], v[140:143], v[164:167], v[60:63]
	v_mfma_f32_16x16x32_bf16 v[60:63], v[144:147], v[168:171], v[60:63]
	s_setprio 0
	s_setprio 1
	v_mfma_f32_16x16x32_bf16 v[56:59], v[148:151], v[164:167], v[56:59]
	v_mfma_f32_16x16x32_bf16 v[56:59], v[152:155], v[168:171], v[56:59]
	v_mfma_f32_16x16x32_bf16 v[40:43], v[148:151], v[172:175], v[40:43]
	v_mfma_f32_16x16x32_bf16 v[40:43], v[152:155], v[176:179], v[40:43]
	v_mfma_f32_16x16x32_bf16 v[24:27], v[148:151], v[180:183], v[24:27]
	v_mfma_f32_16x16x32_bf16 v[24:27], v[152:155], v[184:187], v[24:27]
	v_mfma_f32_16x16x32_bf16 v[8:11], v[148:151], v[188:191], v[8:11]
	v_mfma_f32_16x16x32_bf16 v[8:11], v[152:155], v[192:195], v[8:11]
	s_add_i32 s74, s74, 2
	v_mfma_f32_16x16x32_bf16 v[4:7], v[156:159], v[188:191], v[4:7]
	v_mfma_f32_16x16x32_bf16 v[4:7], v[160:163], v[192:195], v[4:7]
	s_add_u32 s71, s71, 0x100
	s_addc_u32 s73, s73, 0
	v_mfma_f32_16x16x32_bf16 v[20:23], v[156:159], v[180:183], v[20:23]
	v_mfma_f32_16x16x32_bf16 v[20:23], v[160:163], v[184:187], v[20:23]
	s_cmpk_gt_u32 s74, 0x55
	s_mov_b64 s[14:15], s[24:25]
	v_mfma_f32_16x16x32_bf16 v[36:39], v[156:159], v[172:175], v[36:39]
	v_mfma_f32_16x16x32_bf16 v[36:39], v[160:163], v[176:179], v[36:39]
	v_mfma_f32_16x16x32_bf16 v[52:55], v[156:159], v[164:167], v[52:55]
	v_mfma_f32_16x16x32_bf16 v[52:55], v[160:163], v[168:171], v[52:55]
	s_barrier
	s_setprio 0
	s_cbranch_scc0 .LBB0_3195
	s_and_b64 vcc, exec, s[10:11]
	s_cbranch_vccz .LBB0_3198
	s_barrier
